# neighbourhood attention: next-row LDS-DMA pieces issued between the P.V block's bare MFMAs instead of right behind the row barrier
# speedup vs baseline: 1.0107x; 1.0107x over previous
.LBB0_235:
	s_mul_hi_u32 s11, s8, 0x24924925
	s_sub_i32 s74, s8, s11
	s_lshr_b32 s74, s74, 1
	s_add_i32 s74, s74, s11
	s_lshr_b32 s11, s74, 2
	s_add_i32 s74, s6, s87
	s_add_i32 s76, s74, 8
	s_add_i32 s74, s87, 17
	s_min_i32 s74, s74, s95
	v_add_u32_e32 v66, s74, v65
	v_lshlrev_b32_e32 v68, 6, v66
	s_mul_i32 s11, s11, 0x1c000
	v_add_u32_e32 v66, v68, v141
	s_sub_i32 s11, s9, s11
	v_ashrrev_i32_e32 v67, 31, v66
	v_or_b32_e32 v68, v68, v145
	s_waitcnt vmcnt(8) lgkmcnt(0)
	s_barrier
	v_lshlrev_b64 v[66:67], 11, v[66:67]
	v_ashrrev_i32_e32 v69, 31, v68
	s_add_i32 s11, s11, 0
	v_lshl_add_u64 v[206:207], v[150:151], 0, v[66:67]
	v_lshlrev_b64 v[68:69], 11, v[68:69]
	s_add_i32 s100, s11, 0x14000
	s_add_i32 s101, s11, 0x16000
	v_lshl_add_u64 v[208:209], v[152:153], 0, v[68:69]
	s_cmp_lt_u32 s76, s81
	s_cselect_b64 s[74:75], -1, 0
	s_cmp_gt_u32 s76, s3
	s_cselect_b64 s[76:77], -1, 0
	s_or_b64 s[74:75], s[74:75], s[76:77]
	s_and_b64 vcc, exec, s[74:75]
	s_cbranch_vccnz .LBB0_249
	s_mul_hi_u32 s11, s10, 0x24924925
	s_sub_i32 s74, s10, s11
	s_lshr_b32 s74, s74, 1
	s_add_i32 s74, s74, s11
	s_lshr_b32 s11, s74, 2
	s_mul_i32 s11, s11, 0x1c000
	s_sub_i32 s11, s78, s11
	s_add_i32 s11, s11, 0
	v_add_u32_e32 v130, s11, v158
	v_add_u32_e32 v70, v130, v154
	v_add_u32_e32 v126, v130, v159
	ds_read_b128 v[174:177], v70
	ds_read_b128 v[178:181], v70 offset:4096
	v_add_u32_e32 v131, v130, v160
	ds_read_b128 v[182:185], v126
	ds_read_b128 v[186:189], v126 offset:4096
	v_add_u32_e32 v130, v130, v161
	ds_read_b128 v[190:193], v131
	ds_read_b128 v[194:197], v131 offset:4096
	ds_read_b128 v[198:201], v130
	ds_read_b128 v[202:205], v130 offset:4096
	v_readlane_b32 s76, v252, 32
	v_readlane_b32 s77, v252, 33
	v_add_u32_e32 v168, 0, v147
	s_mov_b64 s[74:75], -1
	v_add_u32_e32 v165, 0x20670, v168
	v_add_u32_e32 v164, 0x20678, v168
	v_add_u32_e32 v167, 0x20650, v168
	v_add_u32_e32 v166, 0x20658, v168
	s_and_b64 vcc, exec, s[76:77]
	s_waitcnt lgkmcnt(7)
	v_mfma_f32_32x32x16_bf16 v[82:97], v[174:177], v[98:101], v[32:47]
	s_waitcnt lgkmcnt(6)
	v_mfma_f32_32x32x16_bf16 v[66:81], v[178:181], v[98:101], v[48:63]
	s_waitcnt lgkmcnt(5)
	v_mfma_f32_32x32x16_bf16 v[82:97], v[182:185], v[102:105], v[82:97]
	s_waitcnt lgkmcnt(4)
	v_mfma_f32_32x32x16_bf16 v[66:81], v[186:189], v[102:105], v[66:81]
	s_waitcnt lgkmcnt(3)
	v_mfma_f32_32x32x16_bf16 v[82:97], v[190:193], v[106:109], v[82:97]
	s_waitcnt lgkmcnt(2)
	v_mfma_f32_32x32x16_bf16 v[66:81], v[194:197], v[106:109], v[66:81]
	s_waitcnt lgkmcnt(1)
	v_mfma_f32_32x32x16_bf16 v[82:97], v[198:201], v[110:113], v[82:97]
	s_waitcnt lgkmcnt(0)
	v_mfma_f32_32x32x16_bf16 v[66:81], v[202:205], v[110:113], v[66:81]
	s_cbranch_vccz .LBB0_238
	v_add_u32_e32 v122, 0x20690, v168
	v_add_u32_e32 v124, 0x20698, v168
	v_add_u32_e32 v126, 0x206b0, v168
	v_add_u32_e32 v128, 0x206b8, v168
	v_add_u32_e32 v132, 0x206d0, v168
	v_add_u32_e32 v136, 0x206d8, v168
	ds_read2_b32 v[122:123], v122 offset1:1
	ds_read2_b32 v[124:125], v124 offset1:1
	ds_read2_b32 v[126:127], v126 offset1:1
	ds_read2_b32 v[128:129], v128 offset1:1
	ds_read2_b32 v[130:131], v165 offset1:1
	ds_read2_b32 v[132:133], v132 offset1:1
	ds_read2_b32 v[134:135], v164 offset1:1
	ds_read2_b32 v[136:137], v136 offset1:1
	ds_read2_b32 v[170:171], v167 offset1:1
	ds_read2_b32 v[172:173], v166 offset1:1
	s_mov_b64 s[74:75], 0
	s_waitcnt lgkmcnt(1)
	v_mov_b32_e32 v163, v170
	s_waitcnt lgkmcnt(0)
	v_mov_b32_e32 v169, v172
	s_nop 0
	v_add_f32_e32 v130, v66, v130
	v_exp_f32_e32 v130, v130
	v_add_f32_e32 v131, v67, v131
	v_exp_f32_e32 v131, v131
	v_add_f32_e32 v134, v68, v134
	v_exp_f32_e32 v134, v134
	v_add_f32_e32 v135, v69, v135
	v_exp_f32_e32 v135, v135
	v_add_f32_e32 v70, v70, v122
	v_add_f32_e32 v170, 0, v130
	v_exp_f32_e32 v70, v70
	v_add_f32_e32 v71, v71, v123
	v_add_f32_e32 v170, v131, v170
	v_exp_f32_e32 v71, v71
	v_add_f32_e32 v72, v72, v124
	v_add_f32_e32 v170, v134, v170
	v_exp_f32_e32 v72, v72
	v_add_f32_e32 v73, v73, v125
	v_add_f32_e32 v170, v135, v170
	v_exp_f32_e32 v73, v73
	v_add_f32_e32 v74, v74, v126
	v_add_f32_e32 v122, v70, v170
	v_exp_f32_e32 v74, v74
	v_add_f32_e32 v75, v75, v127
	v_add_f32_e32 v122, v71, v122
	v_exp_f32_e32 v75, v75
	v_add_f32_e32 v76, v76, v128
	v_add_f32_e32 v122, v72, v122
	v_exp_f32_e32 v76, v76
	v_add_f32_e32 v77, v77, v129
	v_add_f32_e32 v122, v73, v122
	v_exp_f32_e32 v77, v77
	v_add_f32_e32 v78, v78, v132
	v_add_f32_e32 v122, v74, v122
	v_exp_f32_e32 v78, v78
	v_add_f32_e32 v79, v79, v133
	v_add_f32_e32 v122, v75, v122
	v_exp_f32_e32 v79, v79
	v_add_f32_e32 v80, v80, v136
	v_add_f32_e32 v122, v76, v122
	v_exp_f32_e32 v80, v80
	v_add_f32_e32 v81, v81, v137
	v_add_f32_e32 v122, v77, v122
	v_exp_f32_e32 v81, v81
	v_add_f32_e32 v123, v94, v163
	v_add_f32_e32 v122, v78, v122
	v_exp_f32_e32 v123, v123
	v_add_f32_e32 v124, v95, v171
	v_add_f32_e32 v122, v79, v122
	v_exp_f32_e32 v124, v124
	v_add_f32_e32 v125, v96, v169
	v_add_f32_e32 v126, v97, v173
	v_add_f32_e32 v122, v80, v122
	v_exp_f32_e32 v125, v125
	v_exp_f32_e32 v126, v126
	v_add_f32_e32 v122, v81, v122
	v_add_f32_e32 v122, v123, v122
	v_add_f32_e32 v122, v124, v122
	v_add_f32_e32 v122, v125, v122
	v_cvt_pk_bf16_f32 v132, v123, v124
	v_cvt_pk_bf16_f32 v133, v125, v126
	v_cvt_pk_bf16_f32 v124, v78, v79
	v_cvt_pk_bf16_f32 v125, v80, v81
	v_add_f32_e32 v163, v126, v122
	v_cvt_pk_bf16_f32 v127, v134, v135
	v_cvt_pk_bf16_f32 v122, v74, v75
	v_cvt_pk_bf16_f32 v123, v76, v77
	v_mov_b64_e32 v[136:137], v[124:125]
	v_cvt_pk_bf16_f32 v126, v130, v131
	v_cvt_pk_bf16_f32 v128, v70, v71
	v_cvt_pk_bf16_f32 v129, v72, v73
	v_mov_b64_e32 v[134:135], v[122:123]

.LBB0_242:
	v_readlane_b32 vcc_lo, v252, 32
	v_readlane_b32 vcc_hi, v252, 33
	s_waitcnt lgkmcnt(8)
	v_mfma_f32_32x32x16_bf16 v[16:31], v[178:181], v[130:133], v[16:31]
	ds_read_b64_tr_b16 v[198:199], v66 offset:14336
	ds_read_b64_tr_b16 v[200:201], v66 offset:14848
	ds_read_b64_tr_b16 v[202:203], v66 offset:15360
	ds_read_b64_tr_b16 v[204:205], v66 offset:15872
	s_mov_b32 s99, m0
	s_mov_b32 m0, s100
	s_nop 0
	global_load_lds_dwordx4 v[206:207], off
	s_mov_b32 m0, s99
	v_cndmask_b32_e64 v67, 0, 1, vcc
	v_cmp_ne_u32_e64 s[76:77], 1, v67
	s_andn2_b64 vcc, exec, vcc
	s_waitcnt lgkmcnt(10)
	v_mfma_f32_32x32x16_bf16 v[16:31], v[182:185], v[126:129], v[16:31]
	s_cbranch_vccnz .LBB0_244
	s_waitcnt lgkmcnt(8)
	v_mfma_f32_32x32x16_bf16 v[16:31], v[186:189], v[134:137], v[16:31]

.LBB0_246:
	s_and_b64 vcc, exec, s[76:77]
	s_waitcnt lgkmcnt(4)
	s_nop 5
	v_mfma_f32_32x32x16_bf16 v[0:15], v[194:197], v[130:133], v[0:15]
	s_mov_b32 s99, m0
	s_mov_b32 m0, s101
	s_nop 0
	global_load_lds_dwordx4 v[208:209], off
	s_mov_b32 m0, s99
	s_waitcnt lgkmcnt(2)
	v_mfma_f32_32x32x16_bf16 v[0:15], v[198:201], v[126:129], v[0:15]
	s_cbranch_vccnz .LBB0_248
	s_waitcnt lgkmcnt(0)
	v_mfma_f32_32x32x16_bf16 v[0:15], v[202:205], v[134:137], v[0:15]

.LBB0_249:
	s_mov_b32 s99, m0
	s_mov_b32 m0, s100
	s_nop 0
	global_load_lds_dwordx4 v[206:207], off
	s_mov_b32 m0, s101
	s_nop 0
	global_load_lds_dwordx4 v[208:209], off
	s_mov_b32 m0, s99
	v_mov_b32_e32 v125, v121
	v_mov_b32_e32 v124, v120
	v_mov_b32_e32 v123, v119
	v_mov_b32_e32 v122, v118
